# RWKV loader: scalar 64-bit bases per chunk instead of VALU address adds, k' as (a*k_a + (1-k_a))*k with 1-k_a kept in registers, LDS buffer offset as an immediate per parity copy (9 fewer VALU per lan
# speedup vs baseline: 1.0024x; 1.0024x over previous
; #define LAS __attribute__((address_space(3)))
; template <bool SAMPLE>
; __device__ __forceinline__ void rwkv_unit(PR P, LAS float* lds, const int b, const int h, const int half, const int wv) {
;     ...
;     const int ltok = (tid - 256) >> 4, lcg = tid & 15; const bool lwave = tid >= 256; const int hch = h * 64 + lcg * 4;
;     const float4 mur = *(const float4*)(P.mu + hch), muk = *(const float4*)(P.mu + 512 + hch), muv = *(const float4*)(P.mu + 1024 + hch);
;     const float4 kk4 = *(const float4*)(P.k_k + hch), ka4 = *(const float4*)(P.k_a + hch);
;     typedef float f32x2 __attribute__((ext_vector_type(2)));
;     const int row0 = half * 32 + (wid & 3) * 8 + (lane >> 4) * 2, cgl = lane & 15, j0 = cgl * 4;
;     f32x2 S[4];
; #pragma unroll
;     for (int c = 0; c < 4; ++c) S[c] = (f32x2){0.f, 0.f};
;     float* sout = P.out + (SAMPLE ? O_WKS : O_WKP) + ((size_t)(b * 8 + h) * 64 + row0) * 64 + j0;
;     if (SAMPLE && wid < 4) { const float* sp = P.state_wkv + ((size_t)(b * 8 + h) * 64 + row0) * 64 + j0; const float4 s0 = *(const float4*)sp, s1 = *(const float4*)(sp + 64);
;         S[0] = (f32x2){s0.x, s1.x}; S[1] = (f32x2){s0.y, s1.y}; S[2] = (f32x2){s0.z, s1.z}; S[3] = (f32x2){s0.w, s1.w}; }
;     LAS float* buf0 = lds; LAS float* buf1 = lds + TC * 384;
;     u32x2 cr[2], ck[2], cv[2], pr[2], pk[2], pv[2], co[2], ca[2];
.LBB0_702:
	s_or_b64 exec, exec, s[8:9]
	v_ashrrev_i32_e32 v57, 6, v56
	s_lshl_b32 s8, s2, 5
	v_lshlrev_b32_e32 v21, 3, v57
	v_lshrrev_b32_e32 v56, 3, v54
	s_and_b32 s8, s8, 32
	v_and_b32_e32 v21, 24, v21
	v_and_b32_e32 v56, 6, v56
	v_and_b32_e32 v66, 15, v54
	v_or3_b32 v54, v56, s8, v21
	v_mov_b32_e32 v56, 0
	v_mov_b32_e32 v21, v56
	v_lshl_add_u64 v[58:59], s[12:13], 0, v[20:21]
	v_lshl_add_u64 v[60:61], s[10:11], 0, v[20:21]
	v_lshl_add_u64 v[62:63], s[14:15], 0, v[20:21]
	v_lshlrev_b32_e32 v20, 1, v54
	s_mov_b32 s71, 0
	v_lshl_add_u64 v[20:21], s[46:47], 0, v[20:21]
	s_lshl_b32 s70, s20, 1
	v_lshl_add_u64 v[20:21], v[20:21], 0, s[70:71]
	s_mov_b64 s[12:13], 0xbae4800
	v_lshlrev_b32_e32 v76, 2, v66
	v_cmp_gt_i32_e64 s[8:9], 4, v57
	v_or_b32_e32 v77, s6, v66
	v_lshl_add_u64 v[64:65], v[20:21], 0, s[12:13]
	v_and_b32_e32 v72, 3, v66
	v_cmp_eq_u32_e64 s[12:13], 0, v72
	v_cmp_eq_u32_e64 s[14:15], 1, v72
	v_cmp_eq_u32_e64 s[16:17], 2, v72
	s_movk_i32 s49, 0x1e00
	s_add_i32 s55, 0, 0xc000
	v_mov_b32_e32 v66, 0
	v_mov_b32_e32 v67, v56
	v_mov_b32_e32 v20, v56
	v_mov_b32_e32 v21, v56
	v_mov_b32_e32 v68, v56
	v_mov_b32_e32 v69, v56
	v_mov_b32_e32 v70, v56
	v_mov_b32_e32 v71, v56
	s_add_u32 s18, s46, 0x3d44800
	s_addc_u32 s19, s47, 0
	s_sub_u32 s20, s18, 0x1e00
	s_subb_u32 s21, s19, 0
	s_add_u32 s22, s46, 0xda04800
	s_addc_u32 s23, s47, 0
	s_add_u32 s24, s46, 0xea84800
	s_addc_u32 s25, s47, 0
	s_bfe_u32 s26, s2, 0x30001
	s_lshl_b32 s26, s26, 7
	v_lshrrev_b32_e32 v123, 1, v75
	v_add_u32_e32 v123, s26, v123
	v_mul_u32_u24_e32 v121, 0x3c00, v55
	v_add_u32_e32 v121, v121, v123
	v_lshl_add_u32 v122, v55, 11, v123
	v_lshl_add_u32 v123, v74, 1, v75
	v_sub_f32_e32 v168, 1.0, v16
	v_sub_f32_e32 v169, 1.0, v17
	v_sub_f32_e32 v170, 1.0, v18
	v_sub_f32_e32 v171, 1.0, v19
	s_cmp_lt_u32 s33, 0x100
	s_cbranch_scc1 .Lld_noprefetch
	s_mov_b32 s29, 1
	s_lshl_b32 s26, s29, 5
	s_add_i32 s26, s26, s6
	s_mul_i32 s98, s26, 0x1e00
	s_lshl_b32 s100, s26, 10
	s_add_u32 s26, s20, s98
	s_addc_u32 s27, s21, 0
	s_add_u32 s28, s24, s100
	s_addc_u32 s29, s25, 0
	s_add_u32 s98, s18, s98
	s_addc_u32 s99, s19, 0
	s_add_u32 s100, s22, s100
	s_addc_u32 s101, s23, 0
	global_load_dwordx2 v[124:125], v121, s[98:99]
	global_load_dwordx2 v[126:127], v121, s[98:99] offset:1024
	global_load_dwordx2 v[128:129], v121, s[98:99] offset:2048
	global_load_dwordx2 v[130:131], v121, s[26:27]
	global_load_dwordx2 v[132:133], v121, s[26:27] offset:1024
	global_load_dwordx2 v[134:135], v121, s[26:27] offset:2048
	global_load_dwordx2 v[136:137], v122, s[100:101]
	global_load_dwordx2 v[138:139], v122, s[28:29]
	s_add_u32 s98, s98, 0x1e00
	s_addc_u32 s99, s99, 0
	s_add_u32 s100, s100, 0x400
	s_addc_u32 s101, s101, 0
	s_add_u32 s28, s28, 0x400
	s_addc_u32 s29, s29, 0
	global_load_dwordx2 v[140:141], v121, s[98:99]
	global_load_dwordx2 v[142:143], v121, s[98:99] offset:1024
	global_load_dwordx2 v[144:145], v121, s[98:99] offset:2048
	global_load_dwordx2 v[152:153], v122, s[100:101]
	global_load_dwordx2 v[154:155], v122, s[28:29]

; #define RW_LOAD(c) do { RW_LOAD1(c, 0); RW_LOAD1(c, 1); } while (0)
; template <bool SAMPLE>
; __device__ __forceinline__ void rwkv_unit(PR P, LAS float* lds, const int b, const int h, const int half, const int wv) {
;     ...
;         if (c + 1 < NCH) RW_LOAD(c + 1);
.LBB0_705:
	s_cmp_lt_u32 s33, 0x100
	s_cbranch_scc1 .Lrw_scan_chunk
	s_add_i32 s56, s71, 1
	s_cmp_eq_u32 s71, 63
	s_cbranch_scc1 .LBB0_704
	s_add_i32 s29, s56, 1
	s_bitcmp1_b32 s71, 0
	s_cbranch_scc1 .Lld_odd
	s_cmp_lt_u32 s29, 64
	s_cbranch_scc0 .Lld_last_even
	s_lshl_b32 s26, s29, 5
	s_add_i32 s26, s26, s6
	s_mul_i32 s98, s26, 0x1e00
	s_lshl_b32 s100, s26, 10
	s_add_u32 s26, s20, s98
	s_addc_u32 s27, s21, 0
	s_add_u32 s28, s24, s100
	s_addc_u32 s29, s25, 0
	s_add_u32 s98, s18, s98
	s_addc_u32 s99, s19, 0
	s_add_u32 s100, s22, s100
	s_addc_u32 s101, s23, 0
	global_load_dwordx2 v[22:23], v121, s[98:99]
	global_load_dwordx2 v[24:25], v121, s[98:99] offset:1024
	global_load_dwordx2 v[26:27], v121, s[98:99] offset:2048
	global_load_dwordx2 v[28:29], v121, s[26:27]
	global_load_dwordx2 v[30:31], v121, s[26:27] offset:1024
	global_load_dwordx2 v[32:33], v121, s[26:27] offset:2048
	global_load_dwordx2 v[34:35], v122, s[100:101]
	global_load_dwordx2 v[36:37], v122, s[28:29]
	s_add_u32 s98, s98, 0x1e00
	s_addc_u32 s99, s99, 0
	s_add_u32 s100, s100, 0x400
	s_addc_u32 s101, s101, 0
	s_add_u32 s28, s28, 0x400
	s_addc_u32 s29, s29, 0
	global_load_dwordx2 v[38:39], v121, s[98:99]
	global_load_dwordx2 v[40:41], v121, s[98:99] offset:1024
	global_load_dwordx2 v[42:43], v121, s[98:99] offset:2048
	global_load_dwordx2 v[50:51], v122, s[100:101]
	global_load_dwordx2 v[52:53], v122, s[28:29]
	s_waitcnt vmcnt(13)
	s_branch .Lld_go_even

.Lld_go_even:
	v_lshlrev_b32_e32 v156, 16, v124
	v_and_b32_e32 v157, 0xffff0000, v124
	v_lshlrev_b32_e32 v158, 16, v125
	v_and_b32_e32 v159, 0xffff0000, v125
	v_lshlrev_b32_e32 v108, 16, v130
	v_and_b32_e32 v109, 0xffff0000, v130
	v_lshlrev_b32_e32 v110, 16, v131
	v_and_b32_e32 v111, 0xffff0000, v131
	v_pk_add_f32 v[108:109], v[108:109], v[156:157] neg_lo:[0,1] neg_hi:[0,1]
	v_pk_add_f32 v[110:111], v[110:111], v[158:159] neg_lo:[0,1] neg_hi:[0,1]
	v_pk_fma_f32 v[84:85], v[0:1], v[108:109], v[156:157]
	v_pk_fma_f32 v[86:87], v[2:3], v[110:111], v[158:159]
	v_lshlrev_b32_e32 v160, 16, v126
	v_and_b32_e32 v161, 0xffff0000, v126
	v_lshlrev_b32_e32 v162, 16, v127
	v_and_b32_e32 v163, 0xffff0000, v127
	v_lshlrev_b32_e32 v108, 16, v132
	v_and_b32_e32 v109, 0xffff0000, v132
	v_lshlrev_b32_e32 v110, 16, v133
	v_and_b32_e32 v111, 0xffff0000, v133
	v_pk_add_f32 v[108:109], v[108:109], v[160:161] neg_lo:[0,1] neg_hi:[0,1]
	v_pk_add_f32 v[110:111], v[110:111], v[162:163] neg_lo:[0,1] neg_hi:[0,1]
	v_pk_fma_f32 v[88:89], v[12:13], v[108:109], v[160:161]
	v_pk_fma_f32 v[90:91], v[14:15], v[110:111], v[162:163]
	v_lshlrev_b32_e32 v164, 16, v128
	v_and_b32_e32 v165, 0xffff0000, v128
	v_lshlrev_b32_e32 v166, 16, v129
	v_and_b32_e32 v167, 0xffff0000, v129
	v_lshlrev_b32_e32 v108, 16, v134
	v_and_b32_e32 v109, 0xffff0000, v134
	v_lshlrev_b32_e32 v110, 16, v135
	v_and_b32_e32 v111, 0xffff0000, v135
	v_pk_add_f32 v[108:109], v[108:109], v[164:165] neg_lo:[0,1] neg_hi:[0,1]
	v_pk_add_f32 v[110:111], v[110:111], v[166:167] neg_lo:[0,1] neg_hi:[0,1]
	v_pk_fma_f32 v[92:93], v[4:5], v[108:109], v[164:165]
	v_pk_fma_f32 v[94:95], v[6:7], v[110:111], v[166:167]
	v_lshlrev_b32_e32 v96, 16, v136
	v_and_b32_e32 v97, 0xffff0000, v136
	v_lshlrev_b32_e32 v98, 16, v137
	v_and_b32_e32 v99, 0xffff0000, v137
	v_lshlrev_b32_e32 v100, 16, v138
	v_and_b32_e32 v101, 0xffff0000, v138
	v_lshlrev_b32_e32 v102, 16, v139
	v_and_b32_e32 v103, 0xffff0000, v139
	v_pk_mul_f32 v[112:113], v[8:9], v[88:89]
	v_pk_mul_f32 v[114:115], v[10:11], v[90:91]
	v_pk_mul_f32 v[104:105], v[112:113], v[112:113]
	v_pk_fma_f32 v[104:105], v[114:115], v[114:115], v[104:105]
	v_add_f32_e32 v104, v104, v105
	v_pk_fma_f32 v[116:117], v[100:101], v[16:17], v[168:169]
	v_pk_fma_f32 v[118:119], v[102:103], v[18:19], v[170:171]
	v_add_f32_dpp v104, v104, v104 quad_perm:[1,0,3,2] row_mask:0xf bank_mask:0xf bound_ctrl:1
	v_pk_mul_f32 v[116:117], v[116:117], v[88:89]
	v_pk_mul_f32 v[118:119], v[118:119], v[90:91]
	v_add_f32_dpp v104, v104, v104 quad_perm:[2,3,0,1] row_mask:0xf bank_mask:0xf bound_ctrl:1
	ds_write_b128 v123, v[84:87] offset:49152
	ds_write_b128 v123, v[96:99] offset:49408
	v_add_f32_dpp v104, v104, v104 row_half_mirror row_mask:0xf bank_mask:0xf bound_ctrl:1
	ds_write_b128 v123, v[116:119] offset:49664
	ds_write_b128 v123, v[92:95] offset:50432
	v_add_f32_dpp v104, v104, v104 row_mirror row_mask:0xf bank_mask:0xf bound_ctrl:1
	v_rsq_f32_e32 v104, v104
	s_nop 0
	v_min_f32_e32 v104, 0x5368d4a5, v104
	v_pk_mul_f32 v[112:113], v[112:113], v[104:105] op_sel_hi:[1,0] neg_lo:[0,1] neg_hi:[0,1]
	v_pk_mul_f32 v[114:115], v[114:115], v[104:105] op_sel_hi:[1,0] neg_lo:[0,1] neg_hi:[0,1]
	ds_write_b128 v123, v[112:115] offset:49920
	v_pk_mul_f32 v[108:109], v[112:113], v[100:101] neg_lo:[1,0] neg_hi:[1,0]
	v_pk_mul_f32 v[110:111], v[114:115], v[102:103] neg_lo:[1,0] neg_hi:[1,0]
	ds_write_b128 v123, v[108:111] offset:50176
	v_lshlrev_b32_e32 v104, 16, v140
	v_and_b32_e32 v105, 0xffff0000, v140
	v_lshlrev_b32_e32 v106, 16, v141
	v_and_b32_e32 v107, 0xffff0000, v141
	v_pk_add_f32 v[108:109], v[156:157], v[104:105] neg_lo:[0,1] neg_hi:[0,1]
	v_pk_add_f32 v[110:111], v[158:159], v[106:107] neg_lo:[0,1] neg_hi:[0,1]
	v_pk_fma_f32 v[84:85], v[0:1], v[108:109], v[104:105]
	v_pk_fma_f32 v[86:87], v[2:3], v[110:111], v[106:107]
	v_lshlrev_b32_e32 v104, 16, v142
	v_and_b32_e32 v105, 0xffff0000, v142
	v_lshlrev_b32_e32 v106, 16, v143
	v_and_b32_e32 v107, 0xffff0000, v143
	v_pk_add_f32 v[108:109], v[160:161], v[104:105] neg_lo:[0,1] neg_hi:[0,1]
	v_pk_add_f32 v[110:111], v[162:163], v[106:107] neg_lo:[0,1] neg_hi:[0,1]
	v_pk_fma_f32 v[88:89], v[12:13], v[108:109], v[104:105]
	v_pk_fma_f32 v[90:91], v[14:15], v[110:111], v[106:107]
	v_lshlrev_b32_e32 v104, 16, v144
	v_and_b32_e32 v105, 0xffff0000, v144
	v_lshlrev_b32_e32 v106, 16, v145
	v_and_b32_e32 v107, 0xffff0000, v145
	v_pk_add_f32 v[108:109], v[164:165], v[104:105] neg_lo:[0,1] neg_hi:[0,1]
	v_pk_add_f32 v[110:111], v[166:167], v[106:107] neg_lo:[0,1] neg_hi:[0,1]
	v_pk_fma_f32 v[92:93], v[4:5], v[108:109], v[104:105]
	v_pk_fma_f32 v[94:95], v[6:7], v[110:111], v[106:107]
	v_lshlrev_b32_e32 v96, 16, v152
	v_and_b32_e32 v97, 0xffff0000, v152
	v_lshlrev_b32_e32 v98, 16, v153
	v_and_b32_e32 v99, 0xffff0000, v153
	v_lshlrev_b32_e32 v100, 16, v154
	v_and_b32_e32 v101, 0xffff0000, v154
	v_lshlrev_b32_e32 v102, 16, v155
	v_and_b32_e32 v103, 0xffff0000, v155
	v_pk_mul_f32 v[112:113], v[8:9], v[88:89]
	v_pk_mul_f32 v[114:115], v[10:11], v[90:91]
	v_pk_mul_f32 v[104:105], v[112:113], v[112:113]
	v_pk_fma_f32 v[104:105], v[114:115], v[114:115], v[104:105]
	v_add_f32_e32 v104, v104, v105
	v_pk_fma_f32 v[116:117], v[100:101], v[16:17], v[168:169]
	v_pk_fma_f32 v[118:119], v[102:103], v[18:19], v[170:171]
	v_add_f32_dpp v104, v104, v104 quad_perm:[1,0,3,2] row_mask:0xf bank_mask:0xf bound_ctrl:1
	v_pk_mul_f32 v[116:117], v[116:117], v[88:89]
	v_pk_mul_f32 v[118:119], v[118:119], v[90:91]
	v_add_f32_dpp v104, v104, v104 quad_perm:[2,3,0,1] row_mask:0xf bank_mask:0xf bound_ctrl:1
	ds_write_b128 v123, v[84:87] offset:50688
	ds_write_b128 v123, v[96:99] offset:50944
	v_add_f32_dpp v104, v104, v104 row_half_mirror row_mask:0xf bank_mask:0xf bound_ctrl:1
	ds_write_b128 v123, v[116:119] offset:51200
	ds_write_b128 v123, v[92:95] offset:51968
	v_add_f32_dpp v104, v104, v104 row_mirror row_mask:0xf bank_mask:0xf bound_ctrl:1
	v_rsq_f32_e32 v104, v104
	s_nop 0
	v_min_f32_e32 v104, 0x5368d4a5, v104
	v_pk_mul_f32 v[112:113], v[112:113], v[104:105] op_sel_hi:[1,0] neg_lo:[0,1] neg_hi:[0,1]
	v_pk_mul_f32 v[114:115], v[114:115], v[104:105] op_sel_hi:[1,0] neg_lo:[0,1] neg_hi:[0,1]
	ds_write_b128 v123, v[112:115] offset:51456
	v_pk_mul_f32 v[108:109], v[112:113], v[100:101] neg_lo:[1,0] neg_hi:[1,0]
	v_pk_mul_f32 v[110:111], v[114:115], v[102:103] neg_lo:[1,0] neg_hi:[1,0]
	ds_write_b128 v123, v[108:111] offset:51712
	s_branch .LBB0_704
; #define RW_LOAD(c) do { RW_LOAD1(c, 0); RW_LOAD1(c, 1); } while (0)
; template <bool SAMPLE>
; __device__ __forceinline__ void rwkv_unit(PR P, LAS float* lds, const int b, const int h, const int half, const int wv) {
;     ...
;         if (c + 1 < NCH) RW_LOAD(c + 1);
.Lld_odd:
	s_cmp_lt_u32 s29, 64
	s_cbranch_scc0 .Lld_last_odd
	s_lshl_b32 s26, s29, 5
	s_add_i32 s26, s26, s6
	s_mul_i32 s98, s26, 0x1e00
	s_lshl_b32 s100, s26, 10
	s_add_u32 s26, s20, s98
	s_addc_u32 s27, s21, 0
	s_add_u32 s28, s24, s100
	s_addc_u32 s29, s25, 0
	s_add_u32 s98, s18, s98
	s_addc_u32 s99, s19, 0
	s_add_u32 s100, s22, s100
	s_addc_u32 s101, s23, 0
	global_load_dwordx2 v[124:125], v121, s[98:99]
	global_load_dwordx2 v[126:127], v121, s[98:99] offset:1024
	global_load_dwordx2 v[128:129], v121, s[98:99] offset:2048
	global_load_dwordx2 v[130:131], v121, s[26:27]
	global_load_dwordx2 v[132:133], v121, s[26:27] offset:1024
	global_load_dwordx2 v[134:135], v121, s[26:27] offset:2048
	global_load_dwordx2 v[136:137], v122, s[100:101]
	global_load_dwordx2 v[138:139], v122, s[28:29]
	s_add_u32 s98, s98, 0x1e00
	s_addc_u32 s99, s99, 0
	s_add_u32 s100, s100, 0x400
	s_addc_u32 s101, s101, 0
	s_add_u32 s28, s28, 0x400
	s_addc_u32 s29, s29, 0
	global_load_dwordx2 v[140:141], v121, s[98:99]
	global_load_dwordx2 v[142:143], v121, s[98:99] offset:1024
	global_load_dwordx2 v[144:145], v121, s[98:99] offset:2048
	global_load_dwordx2 v[152:153], v122, s[100:101]
	global_load_dwordx2 v[154:155], v122, s[28:29]
	s_waitcnt vmcnt(13)
	s_branch .Lld_go_odd

.Lld_go_odd:
	v_lshlrev_b32_e32 v156, 16, v22
	v_and_b32_e32 v157, 0xffff0000, v22
	v_lshlrev_b32_e32 v158, 16, v23
	v_and_b32_e32 v159, 0xffff0000, v23
	v_lshlrev_b32_e32 v108, 16, v28
	v_and_b32_e32 v109, 0xffff0000, v28
	v_lshlrev_b32_e32 v110, 16, v29
	v_and_b32_e32 v111, 0xffff0000, v29
	v_pk_add_f32 v[108:109], v[108:109], v[156:157] neg_lo:[0,1] neg_hi:[0,1]
	v_pk_add_f32 v[110:111], v[110:111], v[158:159] neg_lo:[0,1] neg_hi:[0,1]
	v_pk_fma_f32 v[84:85], v[0:1], v[108:109], v[156:157]
	v_pk_fma_f32 v[86:87], v[2:3], v[110:111], v[158:159]
	v_lshlrev_b32_e32 v160, 16, v24
	v_and_b32_e32 v161, 0xffff0000, v24
	v_lshlrev_b32_e32 v162, 16, v25
	v_and_b32_e32 v163, 0xffff0000, v25
	v_lshlrev_b32_e32 v108, 16, v30
	v_and_b32_e32 v109, 0xffff0000, v30
	v_lshlrev_b32_e32 v110, 16, v31
	v_and_b32_e32 v111, 0xffff0000, v31
	v_pk_add_f32 v[108:109], v[108:109], v[160:161] neg_lo:[0,1] neg_hi:[0,1]
	v_pk_add_f32 v[110:111], v[110:111], v[162:163] neg_lo:[0,1] neg_hi:[0,1]
	v_pk_fma_f32 v[88:89], v[12:13], v[108:109], v[160:161]
	v_pk_fma_f32 v[90:91], v[14:15], v[110:111], v[162:163]
	v_lshlrev_b32_e32 v164, 16, v26
	v_and_b32_e32 v165, 0xffff0000, v26
	v_lshlrev_b32_e32 v166, 16, v27
	v_and_b32_e32 v167, 0xffff0000, v27
	v_lshlrev_b32_e32 v108, 16, v32
	v_and_b32_e32 v109, 0xffff0000, v32
	v_lshlrev_b32_e32 v110, 16, v33
	v_and_b32_e32 v111, 0xffff0000, v33
	v_pk_add_f32 v[108:109], v[108:109], v[164:165] neg_lo:[0,1] neg_hi:[0,1]
	v_pk_add_f32 v[110:111], v[110:111], v[166:167] neg_lo:[0,1] neg_hi:[0,1]
	v_pk_fma_f32 v[92:93], v[4:5], v[108:109], v[164:165]
	v_pk_fma_f32 v[94:95], v[6:7], v[110:111], v[166:167]
	v_lshlrev_b32_e32 v96, 16, v34
	v_and_b32_e32 v97, 0xffff0000, v34
	v_lshlrev_b32_e32 v98, 16, v35
	v_and_b32_e32 v99, 0xffff0000, v35
	v_lshlrev_b32_e32 v100, 16, v36
	v_and_b32_e32 v101, 0xffff0000, v36
	v_lshlrev_b32_e32 v102, 16, v37
	v_and_b32_e32 v103, 0xffff0000, v37
	v_pk_mul_f32 v[112:113], v[8:9], v[88:89]
	v_pk_mul_f32 v[114:115], v[10:11], v[90:91]
	v_pk_mul_f32 v[104:105], v[112:113], v[112:113]
	v_pk_fma_f32 v[104:105], v[114:115], v[114:115], v[104:105]
	v_add_f32_e32 v104, v104, v105
	v_pk_fma_f32 v[116:117], v[100:101], v[16:17], v[168:169]
	v_pk_fma_f32 v[118:119], v[102:103], v[18:19], v[170:171]
	v_add_f32_dpp v104, v104, v104 quad_perm:[1,0,3,2] row_mask:0xf bank_mask:0xf bound_ctrl:1
	v_pk_mul_f32 v[116:117], v[116:117], v[88:89]
	v_pk_mul_f32 v[118:119], v[118:119], v[90:91]
	v_add_f32_dpp v104, v104, v104 quad_perm:[2,3,0,1] row_mask:0xf bank_mask:0xf bound_ctrl:1
	ds_write_b128 v123, v[84:87] offset:0
	ds_write_b128 v123, v[96:99] offset:256
	v_add_f32_dpp v104, v104, v104 row_half_mirror row_mask:0xf bank_mask:0xf bound_ctrl:1
	ds_write_b128 v123, v[116:119] offset:512
	ds_write_b128 v123, v[92:95] offset:1280
	v_add_f32_dpp v104, v104, v104 row_mirror row_mask:0xf bank_mask:0xf bound_ctrl:1
	v_rsq_f32_e32 v104, v104
	s_nop 0
	v_min_f32_e32 v104, 0x5368d4a5, v104
	v_pk_mul_f32 v[112:113], v[112:113], v[104:105] op_sel_hi:[1,0] neg_lo:[0,1] neg_hi:[0,1]
	v_pk_mul_f32 v[114:115], v[114:115], v[104:105] op_sel_hi:[1,0] neg_lo:[0,1] neg_hi:[0,1]
	ds_write_b128 v123, v[112:115] offset:768
	v_pk_mul_f32 v[108:109], v[112:113], v[100:101] neg_lo:[1,0] neg_hi:[1,0]
	v_pk_mul_f32 v[110:111], v[114:115], v[102:103] neg_lo:[1,0] neg_hi:[1,0]
	ds_write_b128 v123, v[108:111] offset:1024
	v_lshlrev_b32_e32 v104, 16, v38
	v_and_b32_e32 v105, 0xffff0000, v38
	v_lshlrev_b32_e32 v106, 16, v39
	v_and_b32_e32 v107, 0xffff0000, v39
	v_pk_add_f32 v[108:109], v[156:157], v[104:105] neg_lo:[0,1] neg_hi:[0,1]
	v_pk_add_f32 v[110:111], v[158:159], v[106:107] neg_lo:[0,1] neg_hi:[0,1]
	v_pk_fma_f32 v[84:85], v[0:1], v[108:109], v[104:105]
	v_pk_fma_f32 v[86:87], v[2:3], v[110:111], v[106:107]
	v_lshlrev_b32_e32 v104, 16, v40
	v_and_b32_e32 v105, 0xffff0000, v40
	v_lshlrev_b32_e32 v106, 16, v41
	v_and_b32_e32 v107, 0xffff0000, v41
	v_pk_add_f32 v[108:109], v[160:161], v[104:105] neg_lo:[0,1] neg_hi:[0,1]
	v_pk_add_f32 v[110:111], v[162:163], v[106:107] neg_lo:[0,1] neg_hi:[0,1]
	v_pk_fma_f32 v[88:89], v[12:13], v[108:109], v[104:105]
	v_pk_fma_f32 v[90:91], v[14:15], v[110:111], v[106:107]
	v_lshlrev_b32_e32 v104, 16, v42
	v_and_b32_e32 v105, 0xffff0000, v42
	v_lshlrev_b32_e32 v106, 16, v43
	v_and_b32_e32 v107, 0xffff0000, v43
	v_pk_add_f32 v[108:109], v[164:165], v[104:105] neg_lo:[0,1] neg_hi:[0,1]
	v_pk_add_f32 v[110:111], v[166:167], v[106:107] neg_lo:[0,1] neg_hi:[0,1]
	v_pk_fma_f32 v[92:93], v[4:5], v[108:109], v[104:105]
	v_pk_fma_f32 v[94:95], v[6:7], v[110:111], v[106:107]
	v_lshlrev_b32_e32 v96, 16, v50
	v_and_b32_e32 v97, 0xffff0000, v50
	v_lshlrev_b32_e32 v98, 16, v51
	v_and_b32_e32 v99, 0xffff0000, v51
	v_lshlrev_b32_e32 v100, 16, v52
	v_and_b32_e32 v101, 0xffff0000, v52
	v_lshlrev_b32_e32 v102, 16, v53
	v_and_b32_e32 v103, 0xffff0000, v53
	v_pk_mul_f32 v[112:113], v[8:9], v[88:89]
	v_pk_mul_f32 v[114:115], v[10:11], v[90:91]
	v_pk_mul_f32 v[104:105], v[112:113], v[112:113]
	v_pk_fma_f32 v[104:105], v[114:115], v[114:115], v[104:105]
	v_add_f32_e32 v104, v104, v105
	v_pk_fma_f32 v[116:117], v[100:101], v[16:17], v[168:169]
	v_pk_fma_f32 v[118:119], v[102:103], v[18:19], v[170:171]
	v_add_f32_dpp v104, v104, v104 quad_perm:[1,0,3,2] row_mask:0xf bank_mask:0xf bound_ctrl:1
	v_pk_mul_f32 v[116:117], v[116:117], v[88:89]
	v_pk_mul_f32 v[118:119], v[118:119], v[90:91]
	v_add_f32_dpp v104, v104, v104 quad_perm:[2,3,0,1] row_mask:0xf bank_mask:0xf bound_ctrl:1
	ds_write_b128 v123, v[84:87] offset:1536
	ds_write_b128 v123, v[96:99] offset:1792
	v_add_f32_dpp v104, v104, v104 row_half_mirror row_mask:0xf bank_mask:0xf bound_ctrl:1
	ds_write_b128 v123, v[116:119] offset:2048
	ds_write_b128 v123, v[92:95] offset:2816
	v_add_f32_dpp v104, v104, v104 row_mirror row_mask:0xf bank_mask:0xf bound_ctrl:1
	v_rsq_f32_e32 v104, v104
	s_nop 0
	v_min_f32_e32 v104, 0x5368d4a5, v104
	v_pk_mul_f32 v[112:113], v[112:113], v[104:105] op_sel_hi:[1,0] neg_lo:[0,1] neg_hi:[0,1]
	v_pk_mul_f32 v[114:115], v[114:115], v[104:105] op_sel_hi:[1,0] neg_lo:[0,1] neg_hi:[0,1]
	ds_write_b128 v123, v[112:115] offset:2304
	v_pk_mul_f32 v[108:109], v[112:113], v[100:101] neg_lo:[1,0] neg_hi:[1,0]
	v_pk_mul_f32 v[110:111], v[114:115], v[102:103] neg_lo:[1,0] neg_hi:[1,0]
	ds_write_b128 v123, v[108:111] offset:2560
	s_branch .LBB0_704
